# v39: v35 + HGRN prompt-item loop chunk-decay broadcast via ds_bpermute (per channel pair, issued at the old readlane position)
# speedup vs baseline: 1.0022x; 1.0022x over previous
.LBB0_594:
	v_mul_f32_e64 v42, |v30|, s80
	v_exp_f32_e32 v42, v42
	v_mul_f32_e64 v43, |v31|, s80
	v_exp_f32_e32 v43, v43
	s_cmpk_lg_i32 s17, 0x1c0
	s_cselect_b32 s60, s42, 0x70
	v_add_f32_e32 v46, 1.0, v42
	s_waitcnt vmcnt(0)
	v_mov_b64_e32 v[28:29], v[20:21]
	s_lshl_b64 s[0:1], s[60:61], 1
	v_rcp_f32_e32 v48, v46
	v_add_f32_e32 v46, 1.0, v43
	v_mov_b64_e32 v[26:27], v[18:19]
	v_lshl_add_u64 v[18:19], v[38:39], 0, s[0:1]
	v_lshl_add_u64 v[22:23], v[40:41], 0, s[0:1]
	v_add_u32_e32 v34, s17, v51
	v_rcp_f32_e32 v49, v46
	global_load_dwordx4 v[18:21], v[18:19], off offset:3072
	v_cmp_nle_f32_e64 s[0:1], 0, v30
	global_load_dwordx4 v[22:25], v[22:23], off
	ds_read_b128 v[80:83], v34
	ds_read_b128 v[34:37], v34 offset:16
	v_pk_mul_f32 v[42:43], v[42:43], v[48:49]
	v_cmp_nle_f32_e32 vcc, 0, v31
	v_cndmask_b32_e64 v79, v48, v42, s[0:1]
	s_waitcnt lgkmcnt(1)
	v_pk_add_f32 v[30:31], v[80:81], 1.0 op_sel_hi:[1,0] neg_lo:[1,0] neg_hi:[1,0]
	v_cndmask_b32_e64 v42, v42, v48, s[0:1]
	v_fma_f32 v79, v30, v79, v80
	v_cndmask_b32_e32 v80, v49, v43, vcc
	v_cndmask_b32_e32 v43, v43, v49, vcc
	v_fma_f32 v48, v31, v80, v81
	v_pk_mul_f32 v[42:43], v[30:31], v[42:43]
	v_mul_f32_e64 v44, |v32|, s80
	v_mov_b32_e32 v30, v79
	s_nop 1
	v_mul_f32_dpp v30, v30, v30 row_shr:1 row_mask:0xf bank_mask:0xf
	v_mov_b32_e32 v31, v48
	s_nop 1
	v_mul_f32_dpp v31, v31, v31 row_shr:1 row_mask:0xf bank_mask:0xf
	v_exp_f32_e32 v54, v44
	v_mul_f32_e64 v44, |v33|, s80
	v_mul_f32_dpp v30, v30, v30 row_shr:2 row_mask:0xf bank_mask:0xf
	v_exp_f32_e32 v55, v44
	v_add_f32_e32 v46, 1.0, v54
	v_mul_f32_dpp v31, v31, v31 row_shr:2 row_mask:0xf bank_mask:0xf
	v_rcp_f32_e32 v86, v46
	v_add_f32_e32 v46, 1.0, v55
	v_mul_f32_dpp v30, v30, v30 row_shr:4 row_mask:0xf bank_mask:0xf
	v_rcp_f32_e32 v87, v46
	v_cmp_nle_f32_e32 vcc, 0, v33
	v_mul_f32_dpp v31, v31, v31 row_shr:4 row_mask:0xf bank_mask:0xf
	v_pk_mul_f32 v[54:55], v[54:55], v[86:87]
	v_mul_f32_e64 v44, |v75|, s80
	v_mul_f32_dpp v30, v30, v30 row_shr:8 row_mask:0xf bank_mask:0xf
	v_exp_f32_e32 v84, v44
	v_mul_f32_e64 v44, |v77|, s80
	v_mul_f32_dpp v31, v31, v31 row_shr:8 row_mask:0xf bank_mask:0xf
	v_exp_f32_e32 v85, v44
	v_add_f32_e32 v46, 1.0, v84
	v_mul_f32_dpp v30, v30, v30 row_bcast:15 row_mask:0xa bank_mask:0xf
	v_rcp_f32_e32 v88, v46
	v_add_f32_e32 v46, 1.0, v85
	v_mul_f32_dpp v31, v31, v31 row_bcast:15 row_mask:0xa bank_mask:0xf
	v_max_f32_e32 v48, 0x554ad2e, v30
	v_max_f32_e32 v49, 0x554ad2e, v31
	v_rcp_f32_e32 v80, v48
	v_rcp_f32_e32 v81, v49
	ds_bpermute_b32 v30, v244, v48
	v_rcp_f32_e32 v89, v46
	v_pk_mul_f32 v[42:43], v[42:43], v[80:81]
	v_lshlrev_b32_e32 v80, 16, v26
	v_and_b32_e32 v81, 0xffff0000, v26
	v_mul_f32_e32 v26, 0xbfb8aa3b, v80
	v_exp_f32_e32 v26, v26
	v_mul_f32_e32 v90, 0xbfb8aa3b, v81
	v_exp_f32_e32 v91, v90
	v_add_f32_e32 v26, 1.0, v26
	v_rcp_f32_e32 v90, v26
	v_add_f32_e32 v26, 1.0, v91
	v_rcp_f32_e32 v91, v26
	ds_bpermute_b32 v31, v244, v49
	v_pk_mul_f32 v[80:81], v[90:91], v[80:81]
	v_cmp_nle_f32_e64 s[0:1], 0, v32
	v_pk_mul_f32 v[48:49], v[80:81], v[48:49]
	v_pk_add_f32 v[32:33], v[82:83], 1.0 op_sel_hi:[1,0] neg_lo:[1,0] neg_hi:[1,0]
	v_cndmask_b32_e64 v26, v86, v54, s[0:1]
	v_cndmask_b32_e32 v80, v87, v55, vcc
	v_cndmask_b32_e32 v55, v55, v87, vcc
	v_cndmask_b32_e64 v54, v54, v86, s[0:1]
	v_fma_f32 v26, v32, v26, v82
	v_pk_mul_f32 v[54:55], v[32:33], v[54:55]
	v_fmac_f32_e32 v83, v33, v80
	v_mul_f32_dpp v26, v26, v26 row_shr:1 row_mask:0xf bank_mask:0xf
	v_cmp_nle_f32_e32 vcc, 0, v77
	v_mov_b32_e32 v32, v83
	s_nop 1
	v_mul_f32_dpp v32, v32, v32 row_shr:1 row_mask:0xf bank_mask:0xf
	v_mul_f32_dpp v26, v26, v26 row_shr:2 row_mask:0xf bank_mask:0xf
	v_mul_f32_e64 v44, |v71|, s80
	v_mul_f32_e64 v45, |v73|, s80
	v_mul_f32_dpp v32, v32, v32 row_shr:2 row_mask:0xf bank_mask:0xf
	v_exp_f32_e32 v44, v44
	v_exp_f32_e32 v45, v45
	v_mul_f32_dpp v26, v26, v26 row_shr:4 row_mask:0xf bank_mask:0xf
	v_add_f32_e32 v46, 1.0, v44
	v_add_f32_e32 v47, 1.0, v45
	v_mul_f32_dpp v32, v32, v32 row_shr:4 row_mask:0xf bank_mask:0xf
	v_rcp_f32_e32 v46, v46
	v_rcp_f32_e32 v47, v47
	v_mul_f32_dpp v26, v26, v26 row_shr:8 row_mask:0xf bank_mask:0xf
	s_waitcnt lgkmcnt(0)
	v_mul_f32_e32 v79, v42, v30
	v_mul_f32_dpp v32, v32, v32 row_shr:8 row_mask:0xf bank_mask:0xf
	v_mul_f32_e32 v90, v43, v31
	v_cvt_pk_bf16_f32 v42, v42, v43
	v_mul_f32_dpp v26, v26, v26 row_bcast:15 row_mask:0xa bank_mask:0xf
	v_max_f32_e32 v80, 0x554ad2e, v26
	v_rcp_f32_e32 v82, v80
	v_mul_f32_dpp v32, v32, v32 row_bcast:15 row_mask:0xa bank_mask:0xf
	v_max_f32_e32 v81, 0x554ad2e, v32
	v_rcp_f32_e32 v83, v81
	ds_bpermute_b32 v32, v244, v80
	v_pk_mul_f32 v[54:55], v[54:55], v[82:83]
	ds_bpermute_b32 v33, v244, v81
	v_lshlrev_b32_e32 v26, 16, v27
	v_and_b32_e32 v27, 0xffff0000, v27
	v_mul_f32_e32 v82, 0xbfb8aa3b, v26
	v_mul_f32_e32 v83, 0xbfb8aa3b, v27
	v_exp_f32_e32 v82, v82
	v_exp_f32_e32 v83, v83
	v_cmp_nle_f32_e64 s[0:1], 0, v75
	v_cvt_pk_bf16_f32 v43, v54, v55
	v_add_f32_e32 v82, 1.0, v82
	v_add_f32_e32 v83, 1.0, v83
	v_rcp_f32_e32 v82, v82
	v_rcp_f32_e32 v83, v83
	s_waitcnt lgkmcnt(0)
	v_mul_f32_e32 v91, v54, v32
	v_mul_f32_e32 v92, v55, v33
	v_pk_mul_f32 v[26:27], v[82:83], v[26:27]
	v_pk_mul_f32 v[80:81], v[26:27], v[80:81]
	v_pk_mul_f32 v[26:27], v[84:85], v[88:89]
	s_waitcnt lgkmcnt(0)
	v_pk_add_f32 v[82:83], v[34:35], 1.0 op_sel_hi:[1,0] neg_lo:[1,0] neg_hi:[1,0]
	v_cndmask_b32_e64 v75, v88, v26, s[0:1]
	v_fma_f32 v34, v82, v75, v34
	v_cndmask_b32_e32 v75, v89, v27, vcc
	v_fma_f32 v35, v83, v75, v35
	v_cndmask_b32_e32 v27, v27, v89, vcc
	v_cndmask_b32_e64 v26, v26, v88, s[0:1]
	v_mul_f32_dpp v34, v34, v34 row_shr:1 row_mask:0xf bank_mask:0xf
	v_pk_mul_f32 v[26:27], v[82:83], v[26:27]
	v_cmp_nle_f32_e32 vcc, 0, v73
	v_mul_f32_dpp v35, v35, v35 row_shr:1 row_mask:0xf bank_mask:0xf
	v_mul_f32_dpp v34, v34, v34 row_shr:2 row_mask:0xf bank_mask:0xf
	s_nop 0
	v_mul_f32_dpp v35, v35, v35 row_shr:2 row_mask:0xf bank_mask:0xf
	v_mul_f32_dpp v34, v34, v34 row_shr:4 row_mask:0xf bank_mask:0xf
	s_nop 0
	v_mul_f32_dpp v35, v35, v35 row_shr:4 row_mask:0xf bank_mask:0xf
	v_mul_f32_dpp v34, v34, v34 row_shr:8 row_mask:0xf bank_mask:0xf
	s_nop 0
	v_mul_f32_dpp v35, v35, v35 row_shr:8 row_mask:0xf bank_mask:0xf
	v_mul_f32_dpp v34, v34, v34 row_bcast:15 row_mask:0xa bank_mask:0xf
	v_max_f32_e32 v82, 0x554ad2e, v34
	v_rcp_f32_e32 v84, v82
	v_mul_f32_dpp v35, v35, v35 row_bcast:15 row_mask:0xa bank_mask:0xf
	v_max_f32_e32 v83, 0x554ad2e, v35
	v_rcp_f32_e32 v85, v83
	ds_bpermute_b32 v34, v244, v82
	v_pk_mul_f32 v[84:85], v[26:27], v[84:85]
	v_lshlrev_b32_e32 v26, 16, v28
	v_and_b32_e32 v27, 0xffff0000, v28
	v_mul_f32_e32 v28, 0xbfb8aa3b, v26
	v_exp_f32_e32 v28, v28
	v_mul_f32_e32 v77, 0xbfb8aa3b, v27
	v_exp_f32_e32 v77, v77
	v_add_f32_e32 v28, 1.0, v28
	v_rcp_f32_e32 v86, v28
	v_add_f32_e32 v28, 1.0, v77
	v_rcp_f32_e32 v87, v28
	ds_bpermute_b32 v35, v244, v83
	v_pk_mul_f32 v[26:27], v[86:87], v[26:27]
	v_pk_mul_f32 v[82:83], v[26:27], v[82:83]
	v_pk_mul_f32 v[26:27], v[44:45], v[46:47]
	v_cmp_nle_f32_e64 s[0:1], 0, v71
	v_pk_add_f32 v[44:45], v[36:37], 1.0 op_sel_hi:[1,0] neg_lo:[1,0] neg_hi:[1,0]
	s_nop 0
	v_cndmask_b32_e64 v28, v46, v26, s[0:1]
	v_fma_f32 v28, v44, v28, v36
	v_cndmask_b32_e32 v36, v47, v27, vcc
	v_fmac_f32_e32 v37, v45, v36
	v_cndmask_b32_e32 v27, v27, v47, vcc
	v_cndmask_b32_e64 v26, v26, v46, s[0:1]
	v_mul_f32_dpp v28, v28, v28 row_shr:1 row_mask:0xf bank_mask:0xf
	v_pk_mul_f32 v[26:27], v[44:45], v[26:27]
	s_waitcnt lgkmcnt(0)
	v_mul_f32_e32 v75, v84, v34
	v_mov_b32_e32 v36, v37
	s_nop 1
	v_mul_f32_dpp v36, v36, v36 row_shr:1 row_mask:0xf bank_mask:0xf
	v_mul_f32_e32 v77, v85, v35
	v_mul_f32_dpp v28, v28, v28 row_shr:2 row_mask:0xf bank_mask:0xf
	v_mul_f32_dpp v36, v36, v36 row_shr:2 row_mask:0xf bank_mask:0xf
	s_nop 0
	v_mul_f32_dpp v28, v28, v28 row_shr:4 row_mask:0xf bank_mask:0xf
	v_mul_f32_dpp v36, v36, v36 row_shr:4 row_mask:0xf bank_mask:0xf
	s_nop 0
	v_mul_f32_dpp v28, v28, v28 row_shr:8 row_mask:0xf bank_mask:0xf
	v_mul_f32_dpp v36, v36, v36 row_shr:8 row_mask:0xf bank_mask:0xf
	s_nop 0
	v_mul_f32_dpp v28, v28, v28 row_bcast:15 row_mask:0xa bank_mask:0xf
	v_max_f32_e32 v44, 0x554ad2e, v28
	v_rcp_f32_e32 v46, v44
	v_mul_f32_dpp v36, v36, v36 row_bcast:15 row_mask:0xa bank_mask:0xf
	v_max_f32_e32 v45, 0x554ad2e, v36
	v_rcp_f32_e32 v47, v45
	ds_bpermute_b32 v36, v244, v44
	v_pk_mul_f32 v[46:47], v[26:27], v[46:47]
	ds_bpermute_b32 v37, v244, v45
	v_lshlrev_b32_e32 v26, 16, v29
	v_and_b32_e32 v27, 0xffff0000, v29
	v_mul_f32_e32 v28, 0xbfb8aa3b, v26
	v_mul_f32_e32 v29, 0xbfb8aa3b, v27
	v_exp_f32_e32 v28, v28
	v_exp_f32_e32 v29, v29
	s_waitcnt lgkmcnt(0)
	v_mul_f32_e32 v71, v46, v36
	v_mul_f32_e32 v73, v47, v37
	v_add_f32_e32 v28, 1.0, v28
	v_add_f32_e32 v29, 1.0, v29
	v_rcp_f32_e32 v28, v28
	v_rcp_f32_e32 v29, v29
	s_nop 0
	v_pk_mul_f32 v[26:27], v[28:29], v[26:27]
	v_pk_mul_f32 v[44:45], v[26:27], v[44:45]
	v_cvt_pk_bf16_f32 v26, v48, v49
	v_cvt_pk_bf16_f32 v29, v44, v45
	v_cvt_pk_bf16_f32 v44, v84, v85
	v_cvt_pk_bf16_f32 v45, v46, v47
	v_cvt_pk_bf16_f32 v27, v80, v81
	v_cvt_pk_bf16_f32 v28, v82, v83
	v_xor_b32_e32 v46, v53, v65
	v_lshl_add_u32 v46, v46, 4, v148
	v_mfma_f32_32x32x16_bf16 v[2:17], v[42:45], v[26:29], v[2:17]
	ds_write_b128 v46, v[26:29] offset:20480
	v_cvt_pk_bf16_f32 v46, v79, v90
	ds_write_b16 v56, v46
	ds_write_b16_d16_hi v56, v46 offset:64
	v_cvt_pk_bf16_f32 v46, v91, v92
	ds_write_b16 v56, v46 offset:128
	ds_write_b16_d16_hi v56, v46 offset:192
	v_cvt_pk_bf16_f32 v46, v75, v77
	ds_write_b16 v56, v46 offset:256
	ds_write_b16_d16_hi v56, v46 offset:320
	v_cvt_pk_bf16_f32 v46, v71, v73
	ds_write_b16 v56, v46 offset:384
	ds_write_b16_d16_hi v56, v46 offset:448
	s_and_saveexec_b64 s[0:1], s[4:5]
	s_cbranch_execz .LBB0_593
	v_add_u32_e32 v26, s17, v183
	ds_write_b128 v26, v[30:33]
	ds_write_b128 v26, v[34:37] offset:16
	s_branch .LBB0_593
